# hy_conv long-sequence tap loop: next step's fragment reads in flight during the current MFMAs (second register set)
# speedup vs baseline: 1.1216x; 1.0049x over previous
.Lconv_lat2:
	v_lshrrev_b32_e32 v193, 7, v176
	s_nop 0
	v_readfirstlane_b32 s101, v193
	v_sub_u32_e32 v193, v61, v35
	s_nop 0
	v_readfirstlane_b32 s100, v193
	s_cmp_eq_u32 s101, 0
	s_cbranch_scc1 .Lcl2_h0
	s_sub_i32 s100, s100, 48
	v_add_u32_e32 v32, 0xffffffd0, v32
	v_add_u32_e32 v33, 0xfffff880, v33
	v_add_u32_e32 v34, 0xfffff400, v34
	v_add_u32_e32 v198, 0xffffec00, v121
	s_branch .Lcl2_go
.Lcl2_h0:
	s_mov_b32 s100, 48
	v_add_u32_e32 v198, 0x1400, v121
.Lcl2_go:
	s_max_i32 s100, s100, 1
	s_min_i32 s100, s100, 0x100
	v_mov_b32_e32 v221, 0x11040
	v_mov_b32_e32 v236, 0
	v_mov_b32_e32 v237, 0
	v_mov_b32_e32 v238, 0
	v_mov_b32_e32 v239, 0
	v_mov_b32_e32 v240, 0
	v_mov_b32_e32 v241, 0
	v_mov_b32_e32 v242, 0
	v_mov_b32_e32 v243, 0
	v_mov_b32_e32 v244, 0
	v_mov_b32_e32 v245, 0
	v_mov_b32_e32 v246, 0
	v_mov_b32_e32 v247, 0
	v_mov_b32_e32 v248, 0
	v_mov_b32_e32 v249, 0
	v_mov_b32_e32 v250, 0
	v_mov_b32_e32 v251, 0
	v_cmp_gt_u32_e32 vcc, s73, v32
	v_lshl_add_u32 v220, v33, 1, v121
	v_lshl_add_u32 v193, v33, 1, v198
	ds_read2_b32 v[36:37], v34 offset1:1
	ds_read2_b32 v[38:39], v34 offset0:2 offset1:3
	ds_read2_b32 v[200:201], v34 offset0:8 offset1:9
	ds_read2_b32 v[202:203], v34 offset0:10 offset1:11
	v_cndmask_b32_e32 v220, v221, v220, vcc
	v_cndmask_b32_e32 v193, v221, v193, vcc
	ds_read_b128 v[40:43], v220
	ds_read_b128 v[44:47], v220 offset:32
	ds_read_b128 v[204:207], v193
	ds_read_b128 v[208:211], v193 offset:32
	v_add_u32_e32 v32, -1, v32
	v_subrev_u32_e32 v33, 40, v33
	v_subrev_u32_e32 v34, 64, v34
.Lcl2_loop:
	v_cmp_gt_u32_e32 vcc, s73, v32
	v_lshl_add_u32 v220, v33, 1, v121
	v_lshl_add_u32 v193, v33, 1, v198
	ds_read2_b32 v[212:213], v34 offset1:1
	ds_read2_b32 v[214:215], v34 offset0:2 offset1:3
	ds_read2_b32 v[216:217], v34 offset0:8 offset1:9
	ds_read2_b32 v[218:219], v34 offset0:10 offset1:11
	v_cndmask_b32_e32 v220, v221, v220, vcc
	v_cndmask_b32_e32 v193, v221, v193, vcc
	ds_read_b128 v[16:19], v220
	ds_read_b128 v[20:23], v220 offset:32
	ds_read_b128 v[24:27], v193
	ds_read_b128 v[28:31], v193 offset:32
	v_add_u32_e32 v32, -1, v32
	v_subrev_u32_e32 v33, 40, v33
	v_subrev_u32_e32 v34, 64, v34
	s_waitcnt lgkmcnt(8)
	v_mfma_f32_32x32x16_bf16 v[0:15], v[36:39], v[40:43], v[0:15]
	v_mfma_f32_32x32x16_bf16 v[236:251], v[36:39], v[204:207], v[236:251]
	v_mfma_f32_32x32x16_bf16 v[0:15], v[200:203], v[44:47], v[0:15]
	v_mfma_f32_32x32x16_bf16 v[236:251], v[200:203], v[208:211], v[236:251]
	s_add_i32 s100, s100, -1
	s_cmp_lg_u32 s100, 0
	s_cbranch_scc0 .Lcl2_done
	v_cmp_gt_u32_e32 vcc, s73, v32
	v_lshl_add_u32 v220, v33, 1, v121
	v_lshl_add_u32 v193, v33, 1, v198
	ds_read2_b32 v[36:37], v34 offset1:1
	ds_read2_b32 v[38:39], v34 offset0:2 offset1:3
	ds_read2_b32 v[200:201], v34 offset0:8 offset1:9
	ds_read2_b32 v[202:203], v34 offset0:10 offset1:11
	v_cndmask_b32_e32 v220, v221, v220, vcc
	v_cndmask_b32_e32 v193, v221, v193, vcc
	ds_read_b128 v[40:43], v220
	ds_read_b128 v[44:47], v220 offset:32
	ds_read_b128 v[204:207], v193
	ds_read_b128 v[208:211], v193 offset:32
	v_add_u32_e32 v32, -1, v32
	v_subrev_u32_e32 v33, 40, v33
	v_subrev_u32_e32 v34, 64, v34
	s_waitcnt lgkmcnt(8)
	v_mfma_f32_32x32x16_bf16 v[0:15], v[212:215], v[16:19], v[0:15]
	v_mfma_f32_32x32x16_bf16 v[236:251], v[212:215], v[24:27], v[236:251]
	v_mfma_f32_32x32x16_bf16 v[0:15], v[216:219], v[20:23], v[0:15]
	v_mfma_f32_32x32x16_bf16 v[236:251], v[216:219], v[28:31], v[236:251]
	s_add_i32 s100, s100, -1
	s_cmp_lg_u32 s100, 0
	s_cbranch_scc1 .Lcl2_loop
.Lcl2_done:
	s_waitcnt lgkmcnt(0)
	s_nop 15
	v_lshrrev_b32_e32 v214, 6, v176
	v_and_b32_e32 v216, 63, v176
	v_lshlrev_b32_e32 v216, 4, v216
	v_lshl_add_u32 v215, v214, 12, v216
	v_xor_b32_e32 v214, 2, v214
	v_lshl_add_u32 v214, v214, 12, v216
	s_barrier
	ds_write_b128 v214, v[236:239] offset:53248
	ds_write_b128 v214, v[240:243] offset:54272
	ds_write_b128 v214, v[244:247] offset:55296
	ds_write_b128 v214, v[248:251] offset:56320
	s_waitcnt lgkmcnt(0)
	s_barrier
	ds_read_b128 v[200:203], v215 offset:53248
	ds_read_b128 v[204:207], v215 offset:54272
	ds_read_b128 v[208:211], v215 offset:55296
	ds_read_b128 v[216:219], v215 offset:56320
	s_waitcnt lgkmcnt(0)
	v_add_f32_e32 v0, v0, v200
	v_add_f32_e32 v1, v1, v201
	v_add_f32_e32 v2, v2, v202
	v_add_f32_e32 v3, v3, v203
	v_add_f32_e32 v4, v4, v204
	v_add_f32_e32 v5, v5, v205
	v_add_f32_e32 v6, v6, v206
	v_add_f32_e32 v7, v7, v207
	v_add_f32_e32 v8, v8, v208
	v_add_f32_e32 v9, v9, v209
	v_add_f32_e32 v10, v10, v210
	v_add_f32_e32 v11, v11, v211
	v_add_f32_e32 v12, v12, v216
	v_add_f32_e32 v13, v13, v217
	v_add_f32_e32 v14, v14, v218
	v_add_f32_e32 v15, v15, v219
	s_branch .Lconv_exit
